# FFN-out residual epilogue rewritten: 3-deep pipelined x loads, saddr addressing, batched ssq reductions
# speedup vs baseline: 1.0083x; 1.0083x over previous
.LBB0_1475:
	s_lshl_b32 s4, s85, 10
	v_lshlrev_b32_e32 v235, 2, v237
	v_add_u32_e32 v235, s4, v235
	v_lshl_add_u32 v234, v179, 12, v235
	s_lshl_b32 s4, s84, 8
	s_add_i32 s4, s4, 0xffffe000
	s_lshr_b32 s4, s4, 10
	s_add_i32 s4, s4, 1
	s_cmp_gt_i32 s84, 31
	s_cselect_b32 s4, s4, 0
	s_mul_i32 s4, s4, 0x9000
	s_add_u32 s12, s56, s4
	s_addc_u32 s13, s57, 0
	global_load_dwordx4 v[130:133], v235, s[12:13]
	global_load_dwordx4 v[134:137], v235, s[12:13] offset:16
	global_load_dwordx4 v[138:141], v235, s[12:13] offset:512
	global_load_dwordx4 v[142:145], v235, s[12:13] offset:528
	s_and_b64 vcc, exec, s[74:75]
	s_cbranch_vccz .Lres_plain_fo
	global_load_dwordx4 v[146:149], v235, s[24:25]
	global_load_dwordx4 v[150:153], v235, s[24:25] offset:16
	global_load_dwordx4 v[154:157], v235, s[24:25] offset:512
	global_load_dwordx4 v[158:161], v235, s[24:25] offset:528
	s_add_u32 s12, s60, s4
	s_addc_u32 s13, s61, 0
	global_load_dwordx4 v[218:221], v235, s[12:13]
	global_load_dwordx4 v[222:225], v235, s[12:13] offset:16
	global_load_dwordx4 v[240:243], v235, s[12:13] offset:512
	global_load_dwordx4 v[244:247], v235, s[12:13] offset:528
	s_add_i32 s4, s84, -32
	s_cmp_gt_i32 s84, 31
	s_cselect_b32 s12, s28, s26
	s_cselect_b32 s13, s29, s27
	s_cselect_b32 s4, s4, s84
	s_lshl_b32 s4, s4, 20
	s_add_u32 s12, s12, s4
	s_addc_u32 s13, s13, 0
	global_load_dwordx4 v[162:165], v234, s[12:13]
	global_load_dwordx4 v[166:169], v234, s[12:13] offset:16
	global_load_dwordx4 v[194:197], v234, s[12:13] offset:512
	global_load_dwordx4 v[198:201], v234, s[12:13] offset:528
	s_add_u32 s12, s12, 0x10000
	s_addc_u32 s13, s13, 0
	global_load_dwordx4 v[202:205], v234, s[12:13]
	global_load_dwordx4 v[206:209], v234, s[12:13] offset:16
	global_load_dwordx4 v[210:213], v234, s[12:13] offset:512
	global_load_dwordx4 v[214:217], v234, s[12:13] offset:528
	s_add_u32 s12, s12, 0x10000
	s_addc_u32 s13, s13, 0
	s_lshl_b32 s4, s84, 20
	s_add_u32 s82, s36, s4
	s_addc_u32 s83, s37, 0
	s_lshl_b32 s4, s84, 10
	s_add_u32 s100, s52, s4
	s_addc_u32 s101, s53, 0
	s_lshl_b32 s4, s84, 19
	s_add_u32 s84, s48, s4
	s_addc_u32 s85, s49, 0
	s_and_b64 vcc, exec, s[70:71]
	s_cbranch_vccz .Lres_al_fo_1
	s_barrier
.Lres_al_fo_1:
	v_lshrrev_b32_e32 v235, 1, v234
	s_waitcnt vmcnt(8)
	v_pk_mul_f32 v[130:131], v[130:131], 0.5 op_sel_hi:[1,0]
	v_pk_mul_f32 v[132:133], v[132:133], 0.5 op_sel_hi:[1,0]
	v_pk_mul_f32 v[134:135], v[134:135], 0.5 op_sel_hi:[1,0]
	v_pk_mul_f32 v[136:137], v[136:137], 0.5 op_sel_hi:[1,0]
	v_pk_mul_f32 v[138:139], v[138:139], 0.5 op_sel_hi:[1,0]
	v_pk_mul_f32 v[140:141], v[140:141], 0.5 op_sel_hi:[1,0]
	v_pk_mul_f32 v[142:143], v[142:143], 0.5 op_sel_hi:[1,0]
	v_pk_mul_f32 v[144:145], v[144:145], 0.5 op_sel_hi:[1,0]
	v_pk_add_f32 v[218:219], v[218:219], 1.0 op_sel_hi:[1,0]
	v_pk_add_f32 v[220:221], v[220:221], 1.0 op_sel_hi:[1,0]
	v_pk_add_f32 v[222:223], v[222:223], 1.0 op_sel_hi:[1,0]
	v_pk_add_f32 v[224:225], v[224:225], 1.0 op_sel_hi:[1,0]
	v_pk_add_f32 v[240:241], v[240:241], 1.0 op_sel_hi:[1,0]
	v_pk_add_f32 v[242:243], v[242:243], 1.0 op_sel_hi:[1,0]
	v_pk_add_f32 v[244:245], v[244:245], 1.0 op_sel_hi:[1,0]
	v_pk_add_f32 v[246:247], v[246:247], 1.0 op_sel_hi:[1,0]
	v_pk_mul_f32 v[146:147], v[146:147], v[218:219]
	v_pk_mul_f32 v[148:149], v[148:149], v[220:221]
	v_pk_mul_f32 v[150:151], v[150:151], v[222:223]
	v_pk_mul_f32 v[152:153], v[152:153], v[224:225]
	v_pk_mul_f32 v[154:155], v[154:155], v[240:241]
	v_pk_mul_f32 v[156:157], v[156:157], v[242:243]
	v_pk_mul_f32 v[158:159], v[158:159], v[244:245]
	v_pk_mul_f32 v[160:161], v[160:161], v[246:247]
	global_load_dwordx4 v[218:221], v234, s[12:13]
	global_load_dwordx4 v[222:225], v234, s[12:13] offset:16
	global_load_dwordx4 v[240:243], v234, s[12:13] offset:512
	global_load_dwordx4 v[244:247], v234, s[12:13] offset:528
	s_add_u32 s12, s12, 0x10000
	s_addc_u32 s13, s13, 0
	s_waitcnt vmcnt(8)
	v_pk_fma_f32 v[122:123], v[122:123], v[130:131], v[162:163]
	v_pk_fma_f32 v[124:125], v[124:125], v[132:133], v[164:165]
	v_pk_fma_f32 v[126:127], v[126:127], v[134:135], v[166:167]
	v_pk_fma_f32 v[128:129], v[128:129], v[136:137], v[168:169]
	v_pk_fma_f32 v[118:119], v[118:119], v[138:139], v[194:195]
	v_pk_fma_f32 v[120:121], v[120:121], v[140:141], v[196:197]
	v_pk_fma_f32 v[114:115], v[114:115], v[142:143], v[198:199]
	v_pk_fma_f32 v[116:117], v[116:117], v[144:145], v[200:201]
	global_load_dwordx4 v[162:165], v234, s[12:13]
	global_load_dwordx4 v[166:169], v234, s[12:13] offset:16
	global_load_dwordx4 v[194:197], v234, s[12:13] offset:512
	global_load_dwordx4 v[198:201], v234, s[12:13] offset:528
	s_add_u32 s12, s12, 0x50000
	s_addc_u32 s13, s13, 0
	global_store_dwordx4 v234, v[122:125], s[82:83]
	global_store_dwordx4 v234, v[126:129], s[82:83] offset:16
	global_store_dwordx4 v234, v[118:121], s[82:83] offset:512
	global_store_dwordx4 v234, v[114:117], s[82:83] offset:528
	s_add_u32 s82, s82, 0x10000
	s_addc_u32 s83, s83, 0
	v_pk_mul_f32 v[248:249], v[122:123], v[122:123]
	v_pk_fma_f32 v[248:249], v[124:125], v[124:125], v[248:249]
	v_pk_fma_f32 v[248:249], v[126:127], v[126:127], v[248:249]
	v_pk_fma_f32 v[248:249], v[128:129], v[128:129], v[248:249]
	v_pk_fma_f32 v[248:249], v[118:119], v[118:119], v[248:249]
	v_pk_fma_f32 v[248:249], v[120:121], v[120:121], v[248:249]
	v_pk_fma_f32 v[248:249], v[114:115], v[114:115], v[248:249]
	v_pk_fma_f32 v[248:249], v[116:117], v[116:117], v[248:249]
	v_pk_mul_f32 v[122:123], v[122:123], v[146:147]
	v_pk_mul_f32 v[124:125], v[124:125], v[148:149]
	v_pk_mul_f32 v[126:127], v[126:127], v[150:151]
	v_pk_mul_f32 v[128:129], v[128:129], v[152:153]
	v_pk_mul_f32 v[118:119], v[118:119], v[154:155]
	v_pk_mul_f32 v[120:121], v[120:121], v[156:157]
	v_pk_mul_f32 v[114:115], v[114:115], v[158:159]
	v_pk_mul_f32 v[116:117], v[116:117], v[160:161]
	v_cvt_pk_bf16_f32 v122, v122, v123
	v_cvt_pk_bf16_f32 v123, v124, v125
	v_cvt_pk_bf16_f32 v124, v126, v127
	v_cvt_pk_bf16_f32 v125, v128, v129
	v_cvt_pk_bf16_f32 v118, v118, v119
	v_cvt_pk_bf16_f32 v119, v120, v121
	v_cvt_pk_bf16_f32 v120, v114, v115
	v_cvt_pk_bf16_f32 v121, v116, v117
	v_add_f32_e32 v126, v248, v249
	global_store_dwordx4 v235, v[122:125], s[84:85]
	global_store_dwordx4 v235, v[118:121], s[84:85] offset:256
	s_add_u32 s84, s84, 0x8000
	s_addc_u32 s85, s85, 0
	s_waitcnt vmcnt(14)
	v_pk_fma_f32 v[110:111], v[110:111], v[130:131], v[202:203]
	v_pk_fma_f32 v[112:113], v[112:113], v[132:133], v[204:205]
	v_pk_fma_f32 v[106:107], v[106:107], v[134:135], v[206:207]
	v_pk_fma_f32 v[108:109], v[108:109], v[136:137], v[208:209]
	v_pk_fma_f32 v[102:103], v[102:103], v[138:139], v[210:211]
	v_pk_fma_f32 v[104:105], v[104:105], v[140:141], v[212:213]
	v_pk_fma_f32 v[98:99], v[98:99], v[142:143], v[214:215]
	v_pk_fma_f32 v[100:101], v[100:101], v[144:145], v[216:217]
	global_load_dwordx4 v[202:205], v234, s[12:13]
	global_load_dwordx4 v[206:209], v234, s[12:13] offset:16
	global_load_dwordx4 v[210:213], v234, s[12:13] offset:512
	global_load_dwordx4 v[214:217], v234, s[12:13] offset:528
	s_add_u32 s12, s12, 0x10000
	s_addc_u32 s13, s13, 0
	global_store_dwordx4 v234, v[110:113], s[82:83]
	global_store_dwordx4 v234, v[106:109], s[82:83] offset:16
	global_store_dwordx4 v234, v[102:105], s[82:83] offset:512
	global_store_dwordx4 v234, v[98:101], s[82:83] offset:528
	s_add_u32 s82, s82, 0x10000
	s_addc_u32 s83, s83, 0
	v_pk_mul_f32 v[248:249], v[110:111], v[110:111]
	v_pk_fma_f32 v[248:249], v[112:113], v[112:113], v[248:249]
	v_pk_fma_f32 v[248:249], v[106:107], v[106:107], v[248:249]
	v_pk_fma_f32 v[248:249], v[108:109], v[108:109], v[248:249]
	v_pk_fma_f32 v[248:249], v[102:103], v[102:103], v[248:249]
	v_pk_fma_f32 v[248:249], v[104:105], v[104:105], v[248:249]
	v_pk_fma_f32 v[248:249], v[98:99], v[98:99], v[248:249]
	v_pk_fma_f32 v[248:249], v[100:101], v[100:101], v[248:249]
	v_pk_mul_f32 v[110:111], v[110:111], v[146:147]
	v_pk_mul_f32 v[112:113], v[112:113], v[148:149]
	v_pk_mul_f32 v[106:107], v[106:107], v[150:151]
	v_pk_mul_f32 v[108:109], v[108:109], v[152:153]
	v_pk_mul_f32 v[102:103], v[102:103], v[154:155]
	v_pk_mul_f32 v[104:105], v[104:105], v[156:157]
	v_pk_mul_f32 v[98:99], v[98:99], v[158:159]
	v_pk_mul_f32 v[100:101], v[100:101], v[160:161]
	v_cvt_pk_bf16_f32 v110, v110, v111
	v_cvt_pk_bf16_f32 v111, v112, v113
	v_cvt_pk_bf16_f32 v112, v106, v107
	v_cvt_pk_bf16_f32 v113, v108, v109
	v_cvt_pk_bf16_f32 v102, v102, v103
	v_cvt_pk_bf16_f32 v103, v104, v105
	v_cvt_pk_bf16_f32 v104, v98, v99
	v_cvt_pk_bf16_f32 v105, v100, v101
	v_add_f32_e32 v106, v248, v249
	global_store_dwordx4 v235, v[110:113], s[84:85]
	global_store_dwordx4 v235, v[102:105], s[84:85] offset:256
	s_add_u32 s84, s84, 0x8000
	s_addc_u32 s85, s85, 0
	s_waitcnt vmcnt(20)
	v_pk_fma_f32 v[94:95], v[94:95], v[130:131], v[218:219]
	v_pk_fma_f32 v[96:97], v[96:97], v[132:133], v[220:221]
	v_pk_fma_f32 v[90:91], v[90:91], v[134:135], v[222:223]
	v_pk_fma_f32 v[92:93], v[92:93], v[136:137], v[224:225]
	v_pk_fma_f32 v[86:87], v[86:87], v[138:139], v[240:241]
	v_pk_fma_f32 v[88:89], v[88:89], v[140:141], v[242:243]
	v_pk_fma_f32 v[82:83], v[82:83], v[142:143], v[244:245]
	v_pk_fma_f32 v[84:85], v[84:85], v[144:145], v[246:247]
	global_load_dwordx4 v[218:221], v234, s[12:13]
	global_load_dwordx4 v[222:225], v234, s[12:13] offset:16
	global_load_dwordx4 v[240:243], v234, s[12:13] offset:512
	global_load_dwordx4 v[244:247], v234, s[12:13] offset:528
	s_add_u32 s12, s12, 0x10000
	s_addc_u32 s13, s13, 0
	global_store_dwordx4 v234, v[94:97], s[82:83]
	global_store_dwordx4 v234, v[90:93], s[82:83] offset:16
	global_store_dwordx4 v234, v[86:89], s[82:83] offset:512
	global_store_dwordx4 v234, v[82:85], s[82:83] offset:528
	s_add_u32 s82, s82, 0x10000
	s_addc_u32 s83, s83, 0
	v_pk_mul_f32 v[248:249], v[94:95], v[94:95]
	v_pk_fma_f32 v[248:249], v[96:97], v[96:97], v[248:249]
	v_pk_fma_f32 v[248:249], v[90:91], v[90:91], v[248:249]
	v_pk_fma_f32 v[248:249], v[92:93], v[92:93], v[248:249]
	v_pk_fma_f32 v[248:249], v[86:87], v[86:87], v[248:249]
	v_pk_fma_f32 v[248:249], v[88:89], v[88:89], v[248:249]
	v_pk_fma_f32 v[248:249], v[82:83], v[82:83], v[248:249]
	v_pk_fma_f32 v[248:249], v[84:85], v[84:85], v[248:249]
	v_pk_mul_f32 v[94:95], v[94:95], v[146:147]
	v_pk_mul_f32 v[96:97], v[96:97], v[148:149]
	v_pk_mul_f32 v[90:91], v[90:91], v[150:151]
	v_pk_mul_f32 v[92:93], v[92:93], v[152:153]
	v_pk_mul_f32 v[86:87], v[86:87], v[154:155]
	v_pk_mul_f32 v[88:89], v[88:89], v[156:157]
	v_pk_mul_f32 v[82:83], v[82:83], v[158:159]
	v_pk_mul_f32 v[84:85], v[84:85], v[160:161]
	v_cvt_pk_bf16_f32 v94, v94, v95
	v_cvt_pk_bf16_f32 v95, v96, v97
	v_cvt_pk_bf16_f32 v96, v90, v91
	v_cvt_pk_bf16_f32 v97, v92, v93
	v_cvt_pk_bf16_f32 v86, v86, v87
	v_cvt_pk_bf16_f32 v87, v88, v89
	v_cvt_pk_bf16_f32 v88, v82, v83
	v_cvt_pk_bf16_f32 v89, v84, v85
	v_add_f32_e32 v90, v248, v249
	global_store_dwordx4 v235, v[94:97], s[84:85]
	global_store_dwordx4 v235, v[86:89], s[84:85] offset:256
	s_add_u32 s84, s84, 0x8000
	s_addc_u32 s85, s85, 0
	s_waitcnt vmcnt(26)
	v_pk_fma_f32 v[78:79], v[78:79], v[130:131], v[162:163]
	v_pk_fma_f32 v[80:81], v[80:81], v[132:133], v[164:165]
	v_pk_fma_f32 v[74:75], v[74:75], v[134:135], v[166:167]
	v_pk_fma_f32 v[76:77], v[76:77], v[136:137], v[168:169]
	v_pk_fma_f32 v[70:71], v[70:71], v[138:139], v[194:195]
	v_pk_fma_f32 v[72:73], v[72:73], v[140:141], v[196:197]
	v_pk_fma_f32 v[66:67], v[66:67], v[142:143], v[198:199]
	v_pk_fma_f32 v[68:69], v[68:69], v[144:145], v[200:201]
	global_load_dwordx4 v[162:165], v234, s[12:13]
	global_load_dwordx4 v[166:169], v234, s[12:13] offset:16
	global_load_dwordx4 v[194:197], v234, s[12:13] offset:512
	global_load_dwordx4 v[198:201], v234, s[12:13] offset:528
	s_add_u32 s12, s12, 0x10000
	s_addc_u32 s13, s13, 0
	global_store_dwordx4 v234, v[78:81], s[82:83]
	global_store_dwordx4 v234, v[74:77], s[82:83] offset:16
	global_store_dwordx4 v234, v[70:73], s[82:83] offset:512
	global_store_dwordx4 v234, v[66:69], s[82:83] offset:528
	s_add_u32 s82, s82, 0x50000
	s_addc_u32 s83, s83, 0
	v_pk_mul_f32 v[248:249], v[78:79], v[78:79]
	v_pk_fma_f32 v[248:249], v[80:81], v[80:81], v[248:249]
	v_pk_fma_f32 v[248:249], v[74:75], v[74:75], v[248:249]
	v_pk_fma_f32 v[248:249], v[76:77], v[76:77], v[248:249]
	v_pk_fma_f32 v[248:249], v[70:71], v[70:71], v[248:249]
	v_pk_fma_f32 v[248:249], v[72:73], v[72:73], v[248:249]
	v_pk_fma_f32 v[248:249], v[66:67], v[66:67], v[248:249]
	v_pk_fma_f32 v[248:249], v[68:69], v[68:69], v[248:249]
	v_pk_mul_f32 v[78:79], v[78:79], v[146:147]
	v_pk_mul_f32 v[80:81], v[80:81], v[148:149]
	v_pk_mul_f32 v[74:75], v[74:75], v[150:151]
	v_pk_mul_f32 v[76:77], v[76:77], v[152:153]
	v_pk_mul_f32 v[70:71], v[70:71], v[154:155]
	v_pk_mul_f32 v[72:73], v[72:73], v[156:157]
	v_pk_mul_f32 v[66:67], v[66:67], v[158:159]
	v_pk_mul_f32 v[68:69], v[68:69], v[160:161]
	v_cvt_pk_bf16_f32 v78, v78, v79
	v_cvt_pk_bf16_f32 v79, v80, v81
	v_cvt_pk_bf16_f32 v80, v74, v75
	v_cvt_pk_bf16_f32 v81, v76, v77
	v_cvt_pk_bf16_f32 v70, v70, v71
	v_cvt_pk_bf16_f32 v71, v72, v73
	v_cvt_pk_bf16_f32 v72, v66, v67
	v_cvt_pk_bf16_f32 v73, v68, v69
	v_add_f32_e32 v74, v248, v249
	global_store_dwordx4 v235, v[78:81], s[84:85]
	global_store_dwordx4 v235, v[70:73], s[84:85] offset:256
	s_add_u32 s84, s84, 0x28000
	s_addc_u32 s85, s85, 0
	s_waitcnt vmcnt(26)
	v_pk_fma_f32 v[62:63], v[62:63], v[130:131], v[202:203]
	v_pk_fma_f32 v[64:65], v[64:65], v[132:133], v[204:205]
	v_pk_fma_f32 v[58:59], v[58:59], v[134:135], v[206:207]
	v_pk_fma_f32 v[60:61], v[60:61], v[136:137], v[208:209]
	v_pk_fma_f32 v[54:55], v[54:55], v[138:139], v[210:211]
	v_pk_fma_f32 v[56:57], v[56:57], v[140:141], v[212:213]
	v_pk_fma_f32 v[50:51], v[50:51], v[142:143], v[214:215]
	v_pk_fma_f32 v[52:53], v[52:53], v[144:145], v[216:217]
	global_load_dwordx4 v[202:205], v234, s[12:13]
	global_load_dwordx4 v[206:209], v234, s[12:13] offset:16
	global_load_dwordx4 v[210:213], v234, s[12:13] offset:512
	global_load_dwordx4 v[214:217], v234, s[12:13] offset:528
	global_store_dwordx4 v234, v[62:65], s[82:83]
	global_store_dwordx4 v234, v[58:61], s[82:83] offset:16
	global_store_dwordx4 v234, v[54:57], s[82:83] offset:512
	global_store_dwordx4 v234, v[50:53], s[82:83] offset:528
	s_add_u32 s82, s82, 0x10000
	s_addc_u32 s83, s83, 0
	v_pk_mul_f32 v[248:249], v[62:63], v[62:63]
	v_pk_fma_f32 v[248:249], v[64:65], v[64:65], v[248:249]
	v_pk_fma_f32 v[248:249], v[58:59], v[58:59], v[248:249]
	v_pk_fma_f32 v[248:249], v[60:61], v[60:61], v[248:249]
	v_pk_fma_f32 v[248:249], v[54:55], v[54:55], v[248:249]
	v_pk_fma_f32 v[248:249], v[56:57], v[56:57], v[248:249]
	v_pk_fma_f32 v[248:249], v[50:51], v[50:51], v[248:249]
	v_pk_fma_f32 v[248:249], v[52:53], v[52:53], v[248:249]
	v_pk_mul_f32 v[62:63], v[62:63], v[146:147]
	v_pk_mul_f32 v[64:65], v[64:65], v[148:149]
	v_pk_mul_f32 v[58:59], v[58:59], v[150:151]
	v_pk_mul_f32 v[60:61], v[60:61], v[152:153]
	v_pk_mul_f32 v[54:55], v[54:55], v[154:155]
	v_pk_mul_f32 v[56:57], v[56:57], v[156:157]
	v_pk_mul_f32 v[50:51], v[50:51], v[158:159]
	v_pk_mul_f32 v[52:53], v[52:53], v[160:161]
	v_cvt_pk_bf16_f32 v62, v62, v63
	v_cvt_pk_bf16_f32 v63, v64, v65
	v_cvt_pk_bf16_f32 v64, v58, v59
	v_cvt_pk_bf16_f32 v65, v60, v61
	v_cvt_pk_bf16_f32 v54, v54, v55
	v_cvt_pk_bf16_f32 v55, v56, v57
	v_cvt_pk_bf16_f32 v56, v50, v51
	v_cvt_pk_bf16_f32 v57, v52, v53
	v_add_f32_e32 v58, v248, v249
	global_store_dwordx4 v235, v[62:65], s[84:85]
	global_store_dwordx4 v235, v[54:57], s[84:85] offset:256
	s_add_u32 s84, s84, 0x8000
	s_addc_u32 s85, s85, 0
	s_waitcnt vmcnt(26)
	v_pk_fma_f32 v[46:47], v[46:47], v[130:131], v[218:219]
	v_pk_fma_f32 v[48:49], v[48:49], v[132:133], v[220:221]
	v_pk_fma_f32 v[42:43], v[42:43], v[134:135], v[222:223]
	v_pk_fma_f32 v[44:45], v[44:45], v[136:137], v[224:225]
	v_pk_fma_f32 v[38:39], v[38:39], v[138:139], v[240:241]
	v_pk_fma_f32 v[40:41], v[40:41], v[140:141], v[242:243]
	v_pk_fma_f32 v[34:35], v[34:35], v[142:143], v[244:245]
	v_pk_fma_f32 v[36:37], v[36:37], v[144:145], v[246:247]
	global_store_dwordx4 v234, v[46:49], s[82:83]
	global_store_dwordx4 v234, v[42:45], s[82:83] offset:16
	global_store_dwordx4 v234, v[38:41], s[82:83] offset:512
	global_store_dwordx4 v234, v[34:37], s[82:83] offset:528
	s_add_u32 s82, s82, 0x10000
	s_addc_u32 s83, s83, 0
	v_pk_mul_f32 v[248:249], v[46:47], v[46:47]
	v_pk_fma_f32 v[248:249], v[48:49], v[48:49], v[248:249]
	v_pk_fma_f32 v[248:249], v[42:43], v[42:43], v[248:249]
	v_pk_fma_f32 v[248:249], v[44:45], v[44:45], v[248:249]
	v_pk_fma_f32 v[248:249], v[38:39], v[38:39], v[248:249]
	v_pk_fma_f32 v[248:249], v[40:41], v[40:41], v[248:249]
	v_pk_fma_f32 v[248:249], v[34:35], v[34:35], v[248:249]
	v_pk_fma_f32 v[248:249], v[36:37], v[36:37], v[248:249]
	v_pk_mul_f32 v[46:47], v[46:47], v[146:147]
	v_pk_mul_f32 v[48:49], v[48:49], v[148:149]
	v_pk_mul_f32 v[42:43], v[42:43], v[150:151]
	v_pk_mul_f32 v[44:45], v[44:45], v[152:153]
	v_pk_mul_f32 v[38:39], v[38:39], v[154:155]
	v_pk_mul_f32 v[40:41], v[40:41], v[156:157]
	v_pk_mul_f32 v[34:35], v[34:35], v[158:159]
	v_pk_mul_f32 v[36:37], v[36:37], v[160:161]
	v_cvt_pk_bf16_f32 v46, v46, v47
	v_cvt_pk_bf16_f32 v47, v48, v49
	v_cvt_pk_bf16_f32 v48, v42, v43
	v_cvt_pk_bf16_f32 v49, v44, v45
	v_cvt_pk_bf16_f32 v38, v38, v39
	v_cvt_pk_bf16_f32 v39, v40, v41
	v_cvt_pk_bf16_f32 v40, v34, v35
	v_cvt_pk_bf16_f32 v41, v36, v37
	v_add_f32_e32 v42, v248, v249
	global_store_dwordx4 v235, v[46:49], s[84:85]
	global_store_dwordx4 v235, v[38:41], s[84:85] offset:256
	s_add_u32 s84, s84, 0x8000
	s_addc_u32 s85, s85, 0
	s_waitcnt vmcnt(22)
	v_pk_fma_f32 v[30:31], v[30:31], v[130:131], v[162:163]
	v_pk_fma_f32 v[32:33], v[32:33], v[132:133], v[164:165]
	v_pk_fma_f32 v[26:27], v[26:27], v[134:135], v[166:167]
	v_pk_fma_f32 v[28:29], v[28:29], v[136:137], v[168:169]
	v_pk_fma_f32 v[22:23], v[22:23], v[138:139], v[194:195]
	v_pk_fma_f32 v[24:25], v[24:25], v[140:141], v[196:197]
	v_pk_fma_f32 v[18:19], v[18:19], v[142:143], v[198:199]
	v_pk_fma_f32 v[20:21], v[20:21], v[144:145], v[200:201]
	global_store_dwordx4 v234, v[30:33], s[82:83]
	global_store_dwordx4 v234, v[26:29], s[82:83] offset:16
	global_store_dwordx4 v234, v[22:25], s[82:83] offset:512
	global_store_dwordx4 v234, v[18:21], s[82:83] offset:528
	s_add_u32 s82, s82, 0x10000
	s_addc_u32 s83, s83, 0
	v_pk_mul_f32 v[248:249], v[30:31], v[30:31]
	v_pk_fma_f32 v[248:249], v[32:33], v[32:33], v[248:249]
	v_pk_fma_f32 v[248:249], v[26:27], v[26:27], v[248:249]
	v_pk_fma_f32 v[248:249], v[28:29], v[28:29], v[248:249]
	v_pk_fma_f32 v[248:249], v[22:23], v[22:23], v[248:249]
	v_pk_fma_f32 v[248:249], v[24:25], v[24:25], v[248:249]
	v_pk_fma_f32 v[248:249], v[18:19], v[18:19], v[248:249]
	v_pk_fma_f32 v[248:249], v[20:21], v[20:21], v[248:249]
	v_pk_mul_f32 v[30:31], v[30:31], v[146:147]
	v_pk_mul_f32 v[32:33], v[32:33], v[148:149]
	v_pk_mul_f32 v[26:27], v[26:27], v[150:151]
	v_pk_mul_f32 v[28:29], v[28:29], v[152:153]
	v_pk_mul_f32 v[22:23], v[22:23], v[154:155]
	v_pk_mul_f32 v[24:25], v[24:25], v[156:157]
	v_pk_mul_f32 v[18:19], v[18:19], v[158:159]
	v_pk_mul_f32 v[20:21], v[20:21], v[160:161]
	v_cvt_pk_bf16_f32 v30, v30, v31
	v_cvt_pk_bf16_f32 v31, v32, v33
	v_cvt_pk_bf16_f32 v32, v26, v27
	v_cvt_pk_bf16_f32 v33, v28, v29
	v_cvt_pk_bf16_f32 v22, v22, v23
	v_cvt_pk_bf16_f32 v23, v24, v25
	v_cvt_pk_bf16_f32 v24, v18, v19
	v_cvt_pk_bf16_f32 v25, v20, v21
	v_add_f32_e32 v26, v248, v249
	global_store_dwordx4 v235, v[30:33], s[84:85]
	global_store_dwordx4 v235, v[22:25], s[84:85] offset:256
	s_add_u32 s84, s84, 0x8000
	s_addc_u32 s85, s85, 0
	s_waitcnt vmcnt(18)
	v_pk_fma_f32 v[14:15], v[14:15], v[130:131], v[202:203]
	v_pk_fma_f32 v[16:17], v[16:17], v[132:133], v[204:205]
	v_pk_fma_f32 v[10:11], v[10:11], v[134:135], v[206:207]
	v_pk_fma_f32 v[12:13], v[12:13], v[136:137], v[208:209]
	v_pk_fma_f32 v[6:7], v[6:7], v[138:139], v[210:211]
	v_pk_fma_f32 v[8:9], v[8:9], v[140:141], v[212:213]
	v_pk_fma_f32 v[2:3], v[2:3], v[142:143], v[214:215]
	v_pk_fma_f32 v[4:5], v[4:5], v[144:145], v[216:217]
	global_store_dwordx4 v234, v[14:17], s[82:83]
	global_store_dwordx4 v234, v[10:13], s[82:83] offset:16
	global_store_dwordx4 v234, v[6:9], s[82:83] offset:512
	global_store_dwordx4 v234, v[2:5], s[82:83] offset:528
	v_pk_mul_f32 v[248:249], v[14:15], v[14:15]
	v_pk_fma_f32 v[248:249], v[16:17], v[16:17], v[248:249]
	v_pk_fma_f32 v[248:249], v[10:11], v[10:11], v[248:249]
	v_pk_fma_f32 v[248:249], v[12:13], v[12:13], v[248:249]
	v_pk_fma_f32 v[248:249], v[6:7], v[6:7], v[248:249]
	v_pk_fma_f32 v[248:249], v[8:9], v[8:9], v[248:249]
	v_pk_fma_f32 v[248:249], v[2:3], v[2:3], v[248:249]
	v_pk_fma_f32 v[248:249], v[4:5], v[4:5], v[248:249]
	v_pk_mul_f32 v[14:15], v[14:15], v[146:147]
	v_pk_mul_f32 v[16:17], v[16:17], v[148:149]
	v_pk_mul_f32 v[10:11], v[10:11], v[150:151]
	v_pk_mul_f32 v[12:13], v[12:13], v[152:153]
	v_pk_mul_f32 v[6:7], v[6:7], v[154:155]
	v_pk_mul_f32 v[8:9], v[8:9], v[156:157]
	v_pk_mul_f32 v[2:3], v[2:3], v[158:159]
	v_pk_mul_f32 v[4:5], v[4:5], v[160:161]
	v_cvt_pk_bf16_f32 v14, v14, v15
	v_cvt_pk_bf16_f32 v15, v16, v17
	v_cvt_pk_bf16_f32 v16, v10, v11
	v_cvt_pk_bf16_f32 v17, v12, v13
	v_cvt_pk_bf16_f32 v6, v6, v7
	v_cvt_pk_bf16_f32 v7, v8, v9
	v_cvt_pk_bf16_f32 v8, v2, v3
	v_cvt_pk_bf16_f32 v9, v4, v5
	v_add_f32_e32 v10, v248, v249
	global_store_dwordx4 v235, v[14:17], s[84:85]
	global_store_dwordx4 v235, v[6:9], s[84:85] offset:256
	v_xor_b32_e32 v250, 16, v232
	v_xor_b32_e32 v251, 32, v232
	v_lshlrev_b32_e32 v250, 2, v250
	v_lshlrev_b32_e32 v251, 2, v251
	ds_bpermute_b32 v162, v250, v126
	ds_bpermute_b32 v163, v250, v106
	ds_bpermute_b32 v164, v250, v90
	ds_bpermute_b32 v165, v250, v74
	ds_bpermute_b32 v166, v250, v58
	ds_bpermute_b32 v167, v250, v42
	ds_bpermute_b32 v168, v250, v26
	ds_bpermute_b32 v169, v250, v10
	s_waitcnt lgkmcnt(0)
	v_add_f32_e32 v126, v126, v162
	v_add_f32_e32 v106, v106, v163
	v_add_f32_e32 v90, v90, v164
	v_add_f32_e32 v74, v74, v165
	v_add_f32_e32 v58, v58, v166
	v_add_f32_e32 v42, v42, v167
	v_add_f32_e32 v26, v26, v168
	v_add_f32_e32 v10, v10, v169
	ds_bpermute_b32 v162, v251, v126
	ds_bpermute_b32 v163, v251, v106
	ds_bpermute_b32 v164, v251, v90
	ds_bpermute_b32 v165, v251, v74
	ds_bpermute_b32 v166, v251, v58
	ds_bpermute_b32 v167, v251, v42
	ds_bpermute_b32 v168, v251, v26
	ds_bpermute_b32 v169, v251, v10
	s_waitcnt lgkmcnt(0)
	v_add_f32_e32 v126, v126, v162
	v_add_f32_e32 v106, v106, v163
	v_add_f32_e32 v90, v90, v164
	v_add_f32_e32 v74, v74, v165
	v_add_f32_e32 v58, v58, v166
	v_add_f32_e32 v42, v42, v167
	v_add_f32_e32 v26, v26, v168
	v_add_f32_e32 v10, v10, v169
	v_lshlrev_b32_e32 v250, 2, v179
	s_and_saveexec_b64 s[12:13], s[8:9]
	global_atomic_add_f32 v250, v126, s[100:101]
	global_atomic_add_f32 v250, v106, s[100:101] offset:64
	global_atomic_add_f32 v250, v90, s[100:101] offset:128
	global_atomic_add_f32 v250, v74, s[100:101] offset:192
	global_atomic_add_f32 v250, v58, s[100:101] offset:512
	global_atomic_add_f32 v250, v42, s[100:101] offset:576
	global_atomic_add_f32 v250, v26, s[100:101] offset:640
	global_atomic_add_f32 v250, v10, s[100:101] offset:704
	s_or_b64 exec, exec, s[12:13]
	s_branch .LBB0_1535
.Lres_plain_fo:
	s_add_i32 s4, s84, -32
	s_cmp_gt_i32 s84, 31
	s_cselect_b32 s12, s28, s26
	s_cselect_b32 s13, s29, s27
	s_cselect_b32 s4, s4, s84
	s_lshl_b32 s4, s4, 20
	s_add_u32 s12, s12, s4
	s_addc_u32 s13, s13, 0
	global_load_dwordx4 v[162:165], v234, s[12:13]
	global_load_dwordx4 v[166:169], v234, s[12:13] offset:16
	global_load_dwordx4 v[194:197], v234, s[12:13] offset:512
	global_load_dwordx4 v[198:201], v234, s[12:13] offset:528
	s_add_u32 s12, s12, 0x10000
	s_addc_u32 s13, s13, 0
	global_load_dwordx4 v[202:205], v234, s[12:13]
	global_load_dwordx4 v[206:209], v234, s[12:13] offset:16
	global_load_dwordx4 v[210:213], v234, s[12:13] offset:512
	global_load_dwordx4 v[214:217], v234, s[12:13] offset:528
	s_add_u32 s12, s12, 0x10000
	s_addc_u32 s13, s13, 0
	s_lshl_b32 s4, s84, 20
	s_add_u32 s82, s36, s4
	s_addc_u32 s83, s37, 0
	s_and_b64 vcc, exec, s[70:71]
	s_cbranch_vccz .Lres_al_fo_0
	s_barrier
.Lres_al_fo_0:
	s_waitcnt vmcnt(8)
	v_pk_mul_f32 v[130:131], v[130:131], 0.5 op_sel_hi:[1,0]
	v_pk_mul_f32 v[132:133], v[132:133], 0.5 op_sel_hi:[1,0]
	v_pk_mul_f32 v[134:135], v[134:135], 0.5 op_sel_hi:[1,0]
	v_pk_mul_f32 v[136:137], v[136:137], 0.5 op_sel_hi:[1,0]
	v_pk_mul_f32 v[138:139], v[138:139], 0.5 op_sel_hi:[1,0]
	v_pk_mul_f32 v[140:141], v[140:141], 0.5 op_sel_hi:[1,0]
	v_pk_mul_f32 v[142:143], v[142:143], 0.5 op_sel_hi:[1,0]
	v_pk_mul_f32 v[144:145], v[144:145], 0.5 op_sel_hi:[1,0]
	global_load_dwordx4 v[218:221], v234, s[12:13]
	global_load_dwordx4 v[222:225], v234, s[12:13] offset:16
	global_load_dwordx4 v[240:243], v234, s[12:13] offset:512
	global_load_dwordx4 v[244:247], v234, s[12:13] offset:528
	s_add_u32 s12, s12, 0x10000
	s_addc_u32 s13, s13, 0
	s_waitcnt vmcnt(8)
	v_pk_fma_f32 v[122:123], v[122:123], v[130:131], v[162:163]
	v_pk_fma_f32 v[124:125], v[124:125], v[132:133], v[164:165]
	v_pk_fma_f32 v[126:127], v[126:127], v[134:135], v[166:167]
	v_pk_fma_f32 v[128:129], v[128:129], v[136:137], v[168:169]
	v_pk_fma_f32 v[118:119], v[118:119], v[138:139], v[194:195]
	v_pk_fma_f32 v[120:121], v[120:121], v[140:141], v[196:197]
	v_pk_fma_f32 v[114:115], v[114:115], v[142:143], v[198:199]
	v_pk_fma_f32 v[116:117], v[116:117], v[144:145], v[200:201]
	global_load_dwordx4 v[162:165], v234, s[12:13]
	global_load_dwordx4 v[166:169], v234, s[12:13] offset:16
	global_load_dwordx4 v[194:197], v234, s[12:13] offset:512
	global_load_dwordx4 v[198:201], v234, s[12:13] offset:528
	s_add_u32 s12, s12, 0x50000
	s_addc_u32 s13, s13, 0
	global_store_dwordx4 v234, v[122:125], s[82:83]
	global_store_dwordx4 v234, v[126:129], s[82:83] offset:16
	global_store_dwordx4 v234, v[118:121], s[82:83] offset:512
	global_store_dwordx4 v234, v[114:117], s[82:83] offset:528
	s_add_u32 s82, s82, 0x10000
	s_addc_u32 s83, s83, 0
	s_waitcnt vmcnt(12)
	v_pk_fma_f32 v[110:111], v[110:111], v[130:131], v[202:203]
	v_pk_fma_f32 v[112:113], v[112:113], v[132:133], v[204:205]
	v_pk_fma_f32 v[106:107], v[106:107], v[134:135], v[206:207]
	v_pk_fma_f32 v[108:109], v[108:109], v[136:137], v[208:209]
	v_pk_fma_f32 v[102:103], v[102:103], v[138:139], v[210:211]
	v_pk_fma_f32 v[104:105], v[104:105], v[140:141], v[212:213]
	v_pk_fma_f32 v[98:99], v[98:99], v[142:143], v[214:215]
	v_pk_fma_f32 v[100:101], v[100:101], v[144:145], v[216:217]
	global_load_dwordx4 v[202:205], v234, s[12:13]
	global_load_dwordx4 v[206:209], v234, s[12:13] offset:16
	global_load_dwordx4 v[210:213], v234, s[12:13] offset:512
	global_load_dwordx4 v[214:217], v234, s[12:13] offset:528
	s_add_u32 s12, s12, 0x10000
	s_addc_u32 s13, s13, 0
	global_store_dwordx4 v234, v[110:113], s[82:83]
	global_store_dwordx4 v234, v[106:109], s[82:83] offset:16
	global_store_dwordx4 v234, v[102:105], s[82:83] offset:512
	global_store_dwordx4 v234, v[98:101], s[82:83] offset:528
	s_add_u32 s82, s82, 0x10000
	s_addc_u32 s83, s83, 0
	s_waitcnt vmcnt(16)
	v_pk_fma_f32 v[94:95], v[94:95], v[130:131], v[218:219]
	v_pk_fma_f32 v[96:97], v[96:97], v[132:133], v[220:221]
	v_pk_fma_f32 v[90:91], v[90:91], v[134:135], v[222:223]
	v_pk_fma_f32 v[92:93], v[92:93], v[136:137], v[224:225]
	v_pk_fma_f32 v[86:87], v[86:87], v[138:139], v[240:241]
	v_pk_fma_f32 v[88:89], v[88:89], v[140:141], v[242:243]
	v_pk_fma_f32 v[82:83], v[82:83], v[142:143], v[244:245]
	v_pk_fma_f32 v[84:85], v[84:85], v[144:145], v[246:247]
	global_load_dwordx4 v[218:221], v234, s[12:13]
	global_load_dwordx4 v[222:225], v234, s[12:13] offset:16
	global_load_dwordx4 v[240:243], v234, s[12:13] offset:512
	global_load_dwordx4 v[244:247], v234, s[12:13] offset:528
	s_add_u32 s12, s12, 0x10000
	s_addc_u32 s13, s13, 0
	global_store_dwordx4 v234, v[94:97], s[82:83]
	global_store_dwordx4 v234, v[90:93], s[82:83] offset:16
	global_store_dwordx4 v234, v[86:89], s[82:83] offset:512
	global_store_dwordx4 v234, v[82:85], s[82:83] offset:528
	s_add_u32 s82, s82, 0x10000
	s_addc_u32 s83, s83, 0
	s_waitcnt vmcnt(20)
	v_pk_fma_f32 v[78:79], v[78:79], v[130:131], v[162:163]
	v_pk_fma_f32 v[80:81], v[80:81], v[132:133], v[164:165]
	v_pk_fma_f32 v[74:75], v[74:75], v[134:135], v[166:167]
	v_pk_fma_f32 v[76:77], v[76:77], v[136:137], v[168:169]
	v_pk_fma_f32 v[70:71], v[70:71], v[138:139], v[194:195]
	v_pk_fma_f32 v[72:73], v[72:73], v[140:141], v[196:197]
	v_pk_fma_f32 v[66:67], v[66:67], v[142:143], v[198:199]
	v_pk_fma_f32 v[68:69], v[68:69], v[144:145], v[200:201]
	global_load_dwordx4 v[162:165], v234, s[12:13]
	global_load_dwordx4 v[166:169], v234, s[12:13] offset:16
	global_load_dwordx4 v[194:197], v234, s[12:13] offset:512
	global_load_dwordx4 v[198:201], v234, s[12:13] offset:528
	s_add_u32 s12, s12, 0x10000
	s_addc_u32 s13, s13, 0
	global_store_dwordx4 v234, v[78:81], s[82:83]
	global_store_dwordx4 v234, v[74:77], s[82:83] offset:16
	global_store_dwordx4 v234, v[70:73], s[82:83] offset:512
	global_store_dwordx4 v234, v[66:69], s[82:83] offset:528
	s_add_u32 s82, s82, 0x50000
	s_addc_u32 s83, s83, 0
	s_waitcnt vmcnt(20)
	v_pk_fma_f32 v[62:63], v[62:63], v[130:131], v[202:203]
	v_pk_fma_f32 v[64:65], v[64:65], v[132:133], v[204:205]
	v_pk_fma_f32 v[58:59], v[58:59], v[134:135], v[206:207]
	v_pk_fma_f32 v[60:61], v[60:61], v[136:137], v[208:209]
	v_pk_fma_f32 v[54:55], v[54:55], v[138:139], v[210:211]
	v_pk_fma_f32 v[56:57], v[56:57], v[140:141], v[212:213]
	v_pk_fma_f32 v[50:51], v[50:51], v[142:143], v[214:215]
	v_pk_fma_f32 v[52:53], v[52:53], v[144:145], v[216:217]
	global_load_dwordx4 v[202:205], v234, s[12:13]
	global_load_dwordx4 v[206:209], v234, s[12:13] offset:16
	global_load_dwordx4 v[210:213], v234, s[12:13] offset:512
	global_load_dwordx4 v[214:217], v234, s[12:13] offset:528
	global_store_dwordx4 v234, v[62:65], s[82:83]
	global_store_dwordx4 v234, v[58:61], s[82:83] offset:16
	global_store_dwordx4 v234, v[54:57], s[82:83] offset:512
	global_store_dwordx4 v234, v[50:53], s[82:83] offset:528
	s_add_u32 s82, s82, 0x10000
	s_addc_u32 s83, s83, 0
	s_waitcnt vmcnt(20)
	v_pk_fma_f32 v[46:47], v[46:47], v[130:131], v[218:219]
	v_pk_fma_f32 v[48:49], v[48:49], v[132:133], v[220:221]
	v_pk_fma_f32 v[42:43], v[42:43], v[134:135], v[222:223]
	v_pk_fma_f32 v[44:45], v[44:45], v[136:137], v[224:225]
	v_pk_fma_f32 v[38:39], v[38:39], v[138:139], v[240:241]
	v_pk_fma_f32 v[40:41], v[40:41], v[140:141], v[242:243]
	v_pk_fma_f32 v[34:35], v[34:35], v[142:143], v[244:245]
	v_pk_fma_f32 v[36:37], v[36:37], v[144:145], v[246:247]
	global_store_dwordx4 v234, v[46:49], s[82:83]
	global_store_dwordx4 v234, v[42:45], s[82:83] offset:16
	global_store_dwordx4 v234, v[38:41], s[82:83] offset:512
	global_store_dwordx4 v234, v[34:37], s[82:83] offset:528
	s_add_u32 s82, s82, 0x10000
	s_addc_u32 s83, s83, 0
	s_waitcnt vmcnt(16)
	v_pk_fma_f32 v[30:31], v[30:31], v[130:131], v[162:163]
	v_pk_fma_f32 v[32:33], v[32:33], v[132:133], v[164:165]
	v_pk_fma_f32 v[26:27], v[26:27], v[134:135], v[166:167]
	v_pk_fma_f32 v[28:29], v[28:29], v[136:137], v[168:169]
	v_pk_fma_f32 v[22:23], v[22:23], v[138:139], v[194:195]
	v_pk_fma_f32 v[24:25], v[24:25], v[140:141], v[196:197]
	v_pk_fma_f32 v[18:19], v[18:19], v[142:143], v[198:199]
	v_pk_fma_f32 v[20:21], v[20:21], v[144:145], v[200:201]
	global_store_dwordx4 v234, v[30:33], s[82:83]
	global_store_dwordx4 v234, v[26:29], s[82:83] offset:16
	global_store_dwordx4 v234, v[22:25], s[82:83] offset:512
	global_store_dwordx4 v234, v[18:21], s[82:83] offset:528
	s_add_u32 s82, s82, 0x10000
	s_addc_u32 s83, s83, 0
	s_waitcnt vmcnt(12)
	v_pk_fma_f32 v[14:15], v[14:15], v[130:131], v[202:203]
	v_pk_fma_f32 v[16:17], v[16:17], v[132:133], v[204:205]
	v_pk_fma_f32 v[10:11], v[10:11], v[134:135], v[206:207]
	v_pk_fma_f32 v[12:13], v[12:13], v[136:137], v[208:209]
	v_pk_fma_f32 v[6:7], v[6:7], v[138:139], v[210:211]
	v_pk_fma_f32 v[8:9], v[8:9], v[140:141], v[212:213]
	v_pk_fma_f32 v[2:3], v[2:3], v[142:143], v[214:215]
	v_pk_fma_f32 v[4:5], v[4:5], v[144:145], v[216:217]
	global_store_dwordx4 v234, v[14:17], s[82:83]
	global_store_dwordx4 v234, v[10:13], s[82:83] offset:16
	global_store_dwordx4 v234, v[6:9], s[82:83] offset:512
	global_store_dwordx4 v234, v[2:5], s[82:83] offset:528

	.amdhsa_kernel _Z8mega_fwd4Args
		.amdhsa_group_segment_fixed_size 0
		.amdhsa_private_segment_fixed_size 0
		.amdhsa_kernarg_size 488
		.amdhsa_user_sgpr_count 2
		.amdhsa_user_sgpr_dispatch_ptr 0
		.amdhsa_user_sgpr_queue_ptr 0
		.amdhsa_user_sgpr_kernarg_segment_ptr 1
		.amdhsa_user_sgpr_dispatch_id 0
		.amdhsa_user_sgpr_kernarg_preload_length 0
		.amdhsa_user_sgpr_kernarg_preload_offset 0
		.amdhsa_user_sgpr_private_segment_size 0
		.amdhsa_uses_dynamic_stack 0
		.amdhsa_enable_private_segment 0
		.amdhsa_system_sgpr_workgroup_id_x 1
		.amdhsa_system_sgpr_workgroup_id_y 0
		.amdhsa_system_sgpr_workgroup_id_z 0
		.amdhsa_system_sgpr_workgroup_info 0
		.amdhsa_system_vgpr_workitem_id 2
		.amdhsa_next_free_vgpr 256
		.amdhsa_next_free_sgpr 102
		.amdhsa_accum_offset 256
		.amdhsa_reserve_vcc 1
		.amdhsa_float_round_mode_32 0
		.amdhsa_float_round_mode_16_64 0
		.amdhsa_float_denorm_mode_32 3
		.amdhsa_float_denorm_mode_16_64 3
		.amdhsa_dx10_clamp 1
		.amdhsa_ieee_mode 1
		.amdhsa_fp16_overflow 0
		.amdhsa_tg_split 0
		.amdhsa_exception_fp_ieee_invalid_op 0
		.amdhsa_exception_fp_denorm_src 0
		.amdhsa_exception_fp_ieee_div_zero 0
		.amdhsa_exception_fp_ieee_overflow 0
		.amdhsa_exception_fp_ieee_underflow 0
		.amdhsa_exception_fp_ieee_inexact 0
		.amdhsa_exception_int_div_zero 0
	.end_amdhsa_kernel

amdhsa.kernels:
  - .agpr_count:     0
    .args:
      - .offset:         0
        .size:           232
        .value_kind:     by_value
      - .offset:         232
        .size:           4
        .value_kind:     hidden_block_count_x
      - .offset:         236
        .size:           4
        .value_kind:     hidden_block_count_y
      - .offset:         240
        .size:           4
        .value_kind:     hidden_block_count_z
      - .offset:         244
        .size:           2
        .value_kind:     hidden_group_size_x
      - .offset:         246
        .size:           2
        .value_kind:     hidden_group_size_y
      - .offset:         248
        .size:           2
        .value_kind:     hidden_group_size_z
      - .offset:         250
        .size:           2
        .value_kind:     hidden_remainder_x
      - .offset:         252
        .size:           2
        .value_kind:     hidden_remainder_y
      - .offset:         254
        .size:           2
        .value_kind:     hidden_remainder_z
      - .offset:         272
        .size:           8
        .value_kind:     hidden_global_offset_x
      - .offset:         280
        .size:           8
        .value_kind:     hidden_global_offset_y
      - .offset:         288
        .size:           8
        .value_kind:     hidden_global_offset_z
      - .offset:         296
        .size:           2
        .value_kind:     hidden_grid_dims
      - .offset:         320
        .size:           8
        .value_kind:     hidden_multigrid_sync_arg
      - .offset:         352
        .size:           4
        .value_kind:     hidden_dynamic_lds_size
    .group_segment_fixed_size: 0
    .kernarg_segment_align: 8
    .kernarg_segment_size: 488
    .language:       OpenCL C
    .language_version:
      - 2
      - 0
    .max_flat_workgroup_size: 512
    .name:           _Z8mega_fwd4Args
    .private_segment_fixed_size: 0
    .sgpr_count:     108
    .sgpr_spill_count: 136
    .symbol:         _Z8mega_fwd4Args.kd
    .uniform_work_group_size: 1
    .uses_dynamic_stack: false
    .vgpr_count:     256
    .vgpr_spill_count: 0
    .wavefront_size: 64
